# FoX tile loop: K/V/c tile loads stay in flight across steps (vote reads c[key0] from the LDS c row instead of a drained global load; counted vmcnt(4) at the LDS stores; loads issued every step; drain
# speedup vs baseline: 1.0057x; 1.0057x over previous
; #define LOADT(i, kreg, vreg, creg) do { const int k0_ = KEY0(i); kreg = *(const u32x4*)(A.K + (size_t)(k0_ + lane) * A.ldkv + wid * 8); vreg = *(const u32x4*)(A.V + (size_t)(k0_ + lane) * A.ldkv + wid * 8); \
;         if (MODE == M_FOX) { if (tid < 64) creg = A.cf[k0_ + tid] * LOG2E; } } while (0)
; template <int MODE>
; __device__ __forceinline__ void attn_unit(LAS unsigned char* lds, const AttnArgs& A, int qb) {
;     ...
;     LOADT(0, k1, v1, c1); if (NT > 1) LOADT(1, k2, v2, c2); if (NT > 2) LOADT(2, k3, v3, c3);
.LBB0_956:
	s_or_b64 exec, exec, s[24:25]
	v_add_u32_e32 v4, s80, v6
	v_mov_b32_e32 v5, 0x40000
	v_lshl_add_u32 v14, v4, 11, v5
	v_mov_b32_e32 v15, v1
	v_lshl_add_u64 v[16:17], s[4:5], 0, v[14:15]
	v_lshl_add_u64 v[14:15], s[8:9], 0, v[14:15]
	v_lshl_add_u64 v[16:17], v[16:17], 0, s[10:11]
	v_lshl_add_u64 v[14:15], v[14:15], 0, s[10:11]
	global_load_dwordx4 v[122:125], v[16:17], off
	global_load_dwordx4 v[126:129], v[14:15], off
	v_mov_b32_e32 v178, 0
	v_mov_b32_e32 v177, 0
	s_and_saveexec_b64 s[24:25], s[6:7]
	s_cbranch_execz .LBB0_958
	v_lshl_add_u64 v[14:15], v[2:3], 0, s[80:81]
	v_lshl_add_u64 v[14:15], v[14:15], 2, s[22:23]
	global_load_dword v5, v[14:15], off offset:512
	s_waitcnt vmcnt(0)
	v_mov_b32_e32 v177, v5
.LBB0_958:
	s_or_b64 exec, exec, s[24:25]
	v_lshl_add_u32 v4, v4, 11, v224
	v_mov_b32_e32 v5, v1
	v_lshl_add_u64 v[14:15], s[4:5], 0, v[4:5]
	v_lshl_add_u64 v[4:5], s[8:9], 0, v[4:5]
	v_lshl_add_u64 v[14:15], v[14:15], 0, s[10:11]
	v_lshl_add_u64 v[4:5], v[4:5], 0, s[10:11]
	global_load_dwordx4 v[130:133], v[14:15], off
	global_load_dwordx4 v[134:137], v[4:5], off
	s_and_saveexec_b64 s[4:5], s[6:7]
	s_cbranch_execz .LBB0_960
	v_lshl_add_u64 v[4:5], v[2:3], 0, s[80:81]
	v_lshl_add_u64 v[4:5], v[4:5], 2, s[22:23]
	global_load_dword v4, v[4:5], off offset:256
	s_waitcnt vmcnt(0)
	v_mov_b32_e32 v178, v4

; #define LOADT(i, kreg, vreg, creg) do { const int k0_ = KEY0(i); kreg = *(const u32x4*)(A.K + (size_t)(k0_ + lane) * A.ldkv + wid * 8); vreg = *(const u32x4*)(A.V + (size_t)(k0_ + lane) * A.ldkv + wid * 8); \
;         if (MODE == M_FOX) { if (tid < 64) creg = A.cf[k0_ + tid] * LOG2E; } } while (0)
; template <int MODE>
; __device__ __forceinline__ void attn_unit(LAS unsigned char* lds, const AttnArgs& A, int qb) {
;     ...
;     for (int i0 = 0; i0 < NT; i0 += 3) {
;         { const int i = i0 + 0; if (i >= NT) break;
;         const int key0 = KEY0(i);
;         if (i + 3 < NT) LOADT(i + 3, k1, v1, c1);
.LBB0_964:
	s_add_i32 s55, s53, -5
	s_cmp_ge_u32 s55, s45
	s_mov_b64 s[10:11], -1
	s_cbranch_scc1 .LBB0_963
	s_add_i32 s0, s53, -2
	s_cmp_lt_u32 s0, s45
	s_cselect_b64 s[24:25], -1, 0
	s_cmp_ge_u32 s0, s45
	v_lshl_add_u64 v[2:3], v[168:169], 0, s[20:21]
	global_load_dwordx4 v[114:117], v[2:3], off
	v_lshl_add_u64 v[2:3], v[170:171], 0, s[20:21]
	global_load_dwordx4 v[118:121], v[2:3], off
	s_and_saveexec_b64 s[10:11], s[6:7]
	s_cbranch_execz .LBB0_968
	global_load_dword v157, v[172:173], off offset:256

; template <int MODE>
; __device__ __forceinline__ void attn_unit(LAS unsigned char* lds, const AttnArgs& A, int qb) {
;     ...
;             else { const float cn = (key0 > 0) ? A.cf[key0 - 1] * LOG2E : 0.f; vote = __all(qb2 + cq2 - cn < m_run - 151.0f) != 0; }
.LBB0_981:
	s_add_i32 s0, s53, -4
	s_cmp_lt_u32 s0, s45
	s_cselect_b64 s[4:5], -1, 0
	s_cmp_ge_u32 s0, s45
	s_cbranch_scc1 .LBB0_985
	v_add_u32_e32 v34, s49, v179
	s_waitcnt vmcnt(4)
	ds_write_b128 v34, v[122:125] offset:17664
	v_add_u32_e32 v34, s50, v181
	s_waitcnt vmcnt(4)
	ds_write_b16 v34, v126 offset:25856
	ds_write_b16_d16_hi v34, v126 offset:26000
	ds_write_b16 v34, v127 offset:26144
	ds_write_b16_d16_hi v34, v127 offset:26288
	ds_write_b16 v34, v128 offset:26432
	ds_write_b16_d16_hi v34, v128 offset:26576
	ds_write_b16 v34, v129 offset:26720
	ds_write_b16_d16_hi v34, v129 offset:26864
	s_and_saveexec_b64 s[10:11], s[6:7]
	v_mul_f32_e32 v177, 0x3fb8aa3b, v177
	ds_write_b32 v183, v177 offset:35072
	s_or_b64 exec, exec, s[10:11]
.LBB0_985:
	s_cmp_lt_i32 s80, 1
	s_cbranch_scc1 .LBB0_987
	s_lshl_b64 s[0:1], s[80:81], 2
	s_add_u32 s0, s22, s0
	s_addc_u32 s1, s23, s1
	ds_read_b32 v34, v1 offset:17408
	s_waitcnt lgkmcnt(0)
	s_branch .LBB0_988

; #define LOADT(i, kreg, vreg, creg) do { const int k0_ = KEY0(i); kreg = *(const u32x4*)(A.K + (size_t)(k0_ + lane) * A.ldkv + wid * 8); vreg = *(const u32x4*)(A.V + (size_t)(k0_ + lane) * A.ldkv + wid * 8); \
;         if (MODE == M_FOX) { if (tid < 64) creg = A.cf[k0_ + tid] * LOG2E; } } while (0)
; template <int MODE>
; __device__ __forceinline__ void attn_unit(LAS unsigned char* lds, const AttnArgs& A, int qb) {
;     ...
;         { const int i = i0 + 1; if (i >= NT) break;
;         const int key0 = KEY0(i);
;         if (i + 3 < NT) LOADT(i + 3, k2, v2, c2);
.LBB0_992:
	s_andn2_b64 vcc, exec, s[4:5]
	s_cbranch_vccnz .LBB0_1002
	s_cmp_ge_u32 s55, s44
	v_lshl_add_u64 v[34:35], v[162:163], 0, s[20:21]
	global_load_dwordx4 v[122:125], v[34:35], off
	v_lshl_add_u64 v[34:35], v[164:165], 0, s[20:21]
	global_load_dwordx4 v[126:129], v[34:35], off
	s_and_saveexec_b64 s[4:5], s[6:7]
	s_cbranch_execz .LBB0_996
	global_load_dword v177, v[172:173], off

; template <int MODE>
; __device__ __forceinline__ void attn_unit(LAS unsigned char* lds, const AttnArgs& A, int qb) {
;     ...
;         if (i + 1 < NT) STORET(2, k3, v3, c3);
.LBB0_1005:
	s_waitcnt vmcnt(4)
	ds_write_b128 v180, v[130:133] offset:35328
	s_waitcnt vmcnt(4)
	ds_write_b16 v182, v134 offset:43520
	ds_write_b16_d16_hi v182, v134 offset:43664
	ds_write_b16 v182, v135 offset:43808
	ds_write_b16_d16_hi v182, v135 offset:43952
	ds_write_b16 v182, v136 offset:44096
	ds_write_b16_d16_hi v182, v136 offset:44240
	ds_write_b16 v182, v137 offset:44384
	ds_write_b16_d16_hi v182, v137 offset:44528
	s_and_saveexec_b64 s[10:11], s[6:7]
	v_mul_f32_e32 v178, 0x3fb8aa3b, v178
	ds_write_b32 v183, v178 offset:52736
	s_or_b64 exec, exec, s[10:11]
	s_cmp_lt_i32 s80, 1
	s_cbranch_scc0 .LBB0_1013

; template <int MODE>
; __device__ __forceinline__ void attn_unit(LAS unsigned char* lds, const AttnArgs& A, int qb) {
;     ...
;             else { const float cn = (key0 > 0) ? A.cf[key0 - 1] * LOG2E : 0.f; vote = __all(qb2 + cq2 - cn < m_run - 151.0f) != 0; }
.LBB0_1013:
	s_lshl_b64 s[0:1], s[80:81], 2
	s_add_u32 s0, s22, s0
	s_addc_u32 s1, s23, s1
	ds_read_b32 v34, v1 offset:35072
	s_waitcnt lgkmcnt(0)

; #define LOADT(i, kreg, vreg, creg) do { const int k0_ = KEY0(i); kreg = *(const u32x4*)(A.K + (size_t)(k0_ + lane) * A.ldkv + wid * 8); vreg = *(const u32x4*)(A.V + (size_t)(k0_ + lane) * A.ldkv + wid * 8); \
;         if (MODE == M_FOX) { if (tid < 64) creg = A.cf[k0_ + tid] * LOG2E; } } while (0)
; template <int MODE>
; __device__ __forceinline__ void attn_unit(LAS unsigned char* lds, const AttnArgs& A, int qb) {
;     ...
;         { const int i = i0 + 2; if (i >= NT) break;
;         const int key0 = KEY0(i);
;         if (i + 3 < NT) LOADT(i + 3, k3, v3, c3);
.LBB0_1017:
	s_add_i32 s0, s53, -3
	s_cmp_ge_u32 s0, s45
	s_mov_b64 s[10:11], 0
	s_cbranch_scc1 .LBB0_1031
	s_cmp_ge_u32 s53, s45
	v_lshl_add_u64 v[34:35], v[174:175], 0, s[20:21]
	global_load_dwordx4 v[130:133], v[34:35], off
	v_lshl_add_u64 v[34:35], v[166:167], 0, s[20:21]
	global_load_dwordx4 v[134:137], v[34:35], off
	s_and_saveexec_b64 s[10:11], s[6:7]
	s_cbranch_execz .LBB0_1021
	global_load_dword v178, v[172:173], off offset:-256

; template <int MODE>
; __device__ __forceinline__ void attn_unit(LAS unsigned char* lds, const AttnArgs& A, int qb) {
;     ...
;         if (i + 1 < NT) STORET(0, k1, v1, c1);
.LBB0_1033:
	s_waitcnt vmcnt(4)
	ds_write_b128 v180, v[114:117]
	s_waitcnt vmcnt(4)
	ds_write_b16 v182, v118 offset:8192
	ds_write_b16_d16_hi v182, v118 offset:8336
	ds_write_b16 v182, v119 offset:8480
	ds_write_b16_d16_hi v182, v119 offset:8624
	ds_write_b16 v182, v120 offset:8768
	ds_write_b16_d16_hi v182, v120 offset:8912
	ds_write_b16 v182, v121 offset:9056
	ds_write_b16_d16_hi v182, v121 offset:9200
	s_and_saveexec_b64 s[4:5], s[6:7]
	v_mul_f32_e32 v157, 0x3fb8aa3b, v157
	ds_write_b32 v183, v157 offset:17408
	s_or_b64 exec, exec, s[4:5]
	s_cmp_lt_i32 s80, 1
	s_cbranch_scc0 .LBB0_1041

; template <int MODE>
; __device__ __forceinline__ void attn_unit(LAS unsigned char* lds, const AttnArgs& A, int qb) {
;     ...
;             else { const float cn = (key0 > 0) ? A.cf[key0 - 1] * LOG2E : 0.f; vote = __all(qb2 + cq2 - cn < m_run - 151.0f) != 0; }
.LBB0_1041:
	s_lshl_b64 s[0:1], s[80:81], 2
	s_add_u32 s0, s22, s0
	s_addc_u32 s1, s23, s1
	ds_read_b32 v34, v1 offset:52736
	s_waitcnt lgkmcnt(0)

; #define LAS __attribute__((address_space(3)))
; #define PVS(s, pk) do { const bf16x8 a0_ = *(const LAS bf16x8*)(vb + (s) * 32), a1_ = *(const LAS bf16x8*)(vb + 32 * VT_STRIDE + (s) * 32); \
;             o0 = __builtin_amdgcn_mfma_f32_32x32x16_bf16(a0_, pk, o0, 0, 0, 0); o1 = __builtin_amdgcn_mfma_f32_32x32x16_bf16(a1_, pk, o1, 0, 0, 0); } while (0)
; #define PVS(s, pk) do { const bf16x8 a0_ = *(const LAS bf16x8*)(vb + (s) * 32), a1_ = *(const LAS bf16x8*)(vb + 32 * VT_STRIDE + (s) * 32); \
;             o0 = __builtin_amdgcn_mfma_f32_32x32x16_bf16(a0_, pk, o0, 0, 0, 0); o1 = __builtin_amdgcn_mfma_f32_32x32x16_bf16(a1_, pk, o1, 0, 0, 0); } while (0)
; #define PVS(s, pk) do { const bf16x8 a0_ = *(const LAS bf16x8*)(vb + (s) * 32), a1_ = *(const LAS bf16x8*)(vb + 32 * VT_STRIDE + (s) * 32); \
;             o0 = __builtin_amdgcn_mfma_f32_32x32x16_bf16(a0_, pk, o0, 0, 0, 0); o1 = __builtin_amdgcn_mfma_f32_32x32x16_bf16(a1_, pk, o1, 0, 0, 0); } while (0)
; #define PVS(s, pk) do { const bf16x8 a0_ = *(const LAS bf16x8*)(vb + (s) * 32), a1_ = *(const LAS bf16x8*)(vb + 32 * VT_STRIDE + (s) * 32); \
;             o0 = __builtin_amdgcn_mfma_f32_32x32x16_bf16(a0_, pk, o0, 0, 0, 0); o1 = __builtin_amdgcn_mfma_f32_32x32x16_bf16(a1_, pk, o1, 0, 0, 0); } while (0)
; #define PVS(s, pk) do { const bf16x8 a0_ = *(const LAS bf16x8*)(vb + (s) * 32), a1_ = *(const LAS bf16x8*)(vb + 32 * VT_STRIDE + (s) * 32); \
;             o0 = __builtin_amdgcn_mfma_f32_32x32x16_bf16(a0_, pk, o0, 0, 0, 0); o1 = __builtin_amdgcn_mfma_f32_32x32x16_bf16(a1_, pk, o1, 0, 0, 0); } while (0)
; #define PVS(s, pk) do { const bf16x8 a0_ = *(const LAS bf16x8*)(vb + (s) * 32), a1_ = *(const LAS bf16x8*)(vb + 32 * VT_STRIDE + (s) * 32); \
;             o0 = __builtin_amdgcn_mfma_f32_32x32x16_bf16(a0_, pk, o0, 0, 0, 0); o1 = __builtin_amdgcn_mfma_f32_32x32x16_bf16(a1_, pk, o1, 0, 0, 0); } while (0)
; template <int MODE>
; __device__ __forceinline__ void attn_unit(LAS unsigned char* lds, const AttnArgs& A, int qb) {
;     ...
;     if (prev_active) {
;         const LAS unsigned char* vb = lds + prevbuf + KB_BYTES + r32 * VT_STRIDE + hi * 16;
;     ...
;         PVS(0, pkP0); PVS(1, pkP1); PVS(2, pkP2); PVS(3, pkP3);
;     ...
;     }
.LBB0_1047:
	s_waitcnt vmcnt(0)
	s_andn2_b64 vcc, exec, s[4:5]
	s_cbranch_vccnz .LBB0_943
	s_add_i32 s0, s2, 0
	v_add3_u32 v0, s0, v185, v0
	ds_read_b128 v[2:5], v0 offset:8192
	s_waitcnt lgkmcnt(0)
	v_mfma_f32_32x32x16_bf16 v[82:97], v[2:5], v[150:153], v[82:97]
	ds_read_b128 v[2:5], v0 offset:12800
	s_waitcnt lgkmcnt(0)
	v_mfma_f32_32x32x16_bf16 v[66:81], v[2:5], v[150:153], v[66:81]
	ds_read_b128 v[2:5], v0 offset:8224
	s_waitcnt lgkmcnt(0)
	v_mfma_f32_32x32x16_bf16 v[82:97], v[2:5], v[142:145], v[82:97]
	ds_read_b128 v[2:5], v0 offset:12832
	s_waitcnt lgkmcnt(0)
	v_mfma_f32_32x32x16_bf16 v[66:81], v[2:5], v[142:145], v[66:81]
	ds_read_b128 v[2:5], v0 offset:8256
	s_waitcnt lgkmcnt(0)
	v_mfma_f32_32x32x16_bf16 v[82:97], v[2:5], v[146:149], v[82:97]
	ds_read_b128 v[2:5], v0 offset:12864
	s_waitcnt lgkmcnt(0)
	v_mfma_f32_32x32x16_bf16 v[66:81], v[2:5], v[146:149], v[66:81]
	ds_read_b128 v[2:5], v0 offset:8288
	s_waitcnt lgkmcnt(0)
	v_mfma_f32_32x32x16_bf16 v[82:97], v[2:5], v[138:141], v[82:97]
	ds_read_b128 v[2:5], v0 offset:12896
	s_waitcnt lgkmcnt(0)
	v_mfma_f32_32x32x16_bf16 v[66:81], v[2:5], v[138:141], v[66:81]
	s_branch .LBB0_943
